# k42: as k39 but the static raise for waves 0-3 is s_setprio 3
# speedup vs baseline: 1.0406x; 1.0013x over previous
; #define LAS __attribute__((address_space(3)))
; #define REFRESH() do { int t_ = threadIdx.x; asm volatile("" : "+v"(t_)); F.tid = t_; F.lane = t_ & 63; F.wave = __builtin_amdgcn_readfirstlane(t_ >> 6); F.gw = blockIdx.x * NWAVES + F.wave; } while (0)
; __global__ void __launch_bounds__(NWAVES * 64, 2) fwd_kernel(Args args) {
;     extern __shared__ __attribute__((aligned(16))) unsigned char lds_raw[];
;     cg::grid_group grid = cg::this_grid();
;     Frame F;
;     F.lds = (LAS unsigned char*)lds_raw;
;     ...
;     F.G = gridDim.x; F.NGW = F.G * NWAVES; REFRESH();
_Z10fwd_kernel4Args:
	s_mov_b32 s42, s2
	s_add_u32 s2, s0, 0xe8
	s_addc_u32 s3, s1, 0
	s_load_dwordx8 s[88:95], s[0:1], 0xc0
	v_writelane_b32 v251, s2, 0
	v_and_b32_e32 v206, 0x3ff, v0
	v_mov_b32_e32 v1, v206
	v_readfirstlane_b32 s100, v206
	s_nop 3
	s_lshr_b32 s100, s100, 8
	s_cmp_eq_u32 s100, 0
	s_cbranch_scc0 .Lprio_done
	s_setprio 3
